# ps1 + prompt-diff main-loop LDS-DMA loads use SGPR base + 32-bit lane offset addressing (no 64-bit VALU address add per piece)
# speedup vs baseline: 1.0099x; 1.0099x over previous
; #define TWAIT_BAR(N) asm volatile("s_waitcnt vmcnt(" #N ") lgkmcnt(0)\n\ts_barrier" ::: "memory")
; #define TMX3(a, b, c) __builtin_fmaxf(__builtin_fmaxf((a), (b)), (c))
; #define TEX(v) __builtin_amdgcn_exp2f(v)
; #define DMA_K(t, slot) glds16(ksrc + (size_t)(t) * 64 * 512, (unsigned)__builtin_amdgcn_readfirstlane(kdst + (slot)))
; #define DMA_V(t, slot) glds16(vsrc + (size_t)(t) * 64 * 512, (unsigned)__builtin_amdgcn_readfirstlane(vdst + (slot)))
; #define ROT() do { sl_prev = sl_cur; sl_cur = sl_next; sl_next = (sl_next == 2 * SLOTB) ? 0 : sl_next + SLOTB; } while (0)
; #define DMA_K(t, slot) glds16(ksrc + (size_t)(t) * 64 * 512, (unsigned)__builtin_amdgcn_readfirstlane(kdst + (slot)))
; #define DMA_V(t, slot) do { glds16(vsrc + (size_t)(t) * 64 * 512, (unsigned)__builtin_amdgcn_readfirstlane(vdst + (slot))); glds16(vsrc + (size_t)(t) * 64 * 512 + 64, (unsigned)__builtin_amdgcn_readfirstlane(vdst + (slot) + 8192)); } while (0)
; #define ROT() do { sl_prev = sl_cur; sl_cur = sl_next; sl_next = (sl_next == 2) ? 0 : sl_next + 1; } while (0)
; template <bool NOMAX>
; __device__ __forceinline__ void diff_unit(const AttnCtx& C, int u, LAS unsigned char* lds) {
;     ...
;         if constexpr (NOMAX) {
; #pragma unroll
;             for (int r = 0; r < 16; ++r) { pA0[r] = TEX(pA0[r]); pA1[r] = TEX(pA1[r]); }
;         } else {
;         float rm = TMX3(pA0[0], pA0[1], pA1[0]);
; #pragma unroll
;         for (int r = 1; r < 16; ++r) rm = TMX3(rm, pA0[r], pA1[r]);
;         { auto rr = __builtin_amdgcn_permlane32_swap(__float_as_uint(rm), __float_as_uint(rm), false, false); rm = __builtin_fmaxf(__uint_as_float(rr[0]), __uint_as_float(rr[1])); }
;         nm -= rm;
; #pragma unroll
;         for (int r = 0; r < 16; ++r) { pA0[r] = TEX(pA0[r] - rm); pA1[r] = TEX(pA1[r] - rm); }
;         }
;     }
;     TWAIT_BAR(0);
;     DMA_K(3, 0); DMA_V(1, VSLOT);
;     ROT();
;     kload8(kf, kp0 + sl_cur * SLOTB);
;     TWAIT_BAR(3);
;     s16x4 vl0, vh0, vl1, vh1, vl2, vh2, vl3, vh3; v4u pw0, pw1, pw2, pw3;
;     bf16x8 qa = QRD(0), qb_;
.LBB0_461:
	v_lshlrev_b32_e32 v2, 1, v6
	v_and_b32_e32 v2, 32, v2
	v_lshlrev_b32_e32 v8, 4, v6
	v_add3_u32 v2, 0, v2, v7
	v_lshlrev_b32_e32 v7, 8, v211
	v_and_b32_e32 v8, 0xc0, v8
	s_waitcnt vmcnt(0) lgkmcnt(0)
	s_barrier
	v_add3_u32 v214, v2, v7, v8
	v_lshl_add_u64 v[8:9], v[204:205], 0, s[24:25]
	s_mov_b32 s6, m0
	s_mov_b32 m0, s49
	s_nop 0
	global_load_lds_dwordx4 v[8:9], off
	s_mov_b32 m0, s6
	v_lshl_add_u64 v[8:9], v[4:5], 0, s[20:21]
	s_add_i32 s6, s49, 0xa000
	s_mov_b32 s7, m0
	s_mov_b32 m0, s6
	s_nop 0
	global_load_lds_dwordx4 v[8:9], off
	s_mov_b32 m0, s7
	v_lshl_add_u64 v[4:5], v[4:5], 0, s[26:27]
	s_add_i32 s6, s49, 0xc000
	s_mov_b32 s7, m0
	s_mov_b32 m0, s6
	s_nop 0
	global_load_lds_dwordx4 v[4:5], off
	s_mov_b32 m0, s7
	ds_read_b128 v[192:195], v222 offset:8192
	ds_read_b128 v[184:187], v222 offset:8704
	ds_read_b128 v[188:191], v222 offset:10240
	ds_read_b128 v[180:183], v222 offset:10752
	ds_read_b128 v[176:179], v222 offset:12288
	ds_read_b128 v[172:175], v222 offset:12800
	ds_read_b128 v[168:171], v222 offset:14336
	ds_read_b128 v[164:167], v222 offset:14848
	s_waitcnt vmcnt(3) lgkmcnt(0)
	s_barrier
	ds_read_b128 v[116:119], v219
	v_exp_f32_e32 v100, v36
	v_exp_f32_e32 v84, v20
	v_exp_f32_e32 v101, v37
	v_exp_f32_e32 v85, v21
	v_exp_f32_e32 v102, v38
	v_exp_f32_e32 v86, v22
	v_exp_f32_e32 v103, v39
	v_exp_f32_e32 v87, v23
	v_exp_f32_e32 v104, v40
	v_exp_f32_e32 v88, v24
	v_exp_f32_e32 v105, v41
	v_exp_f32_e32 v89, v25
	v_exp_f32_e32 v106, v42
	v_exp_f32_e32 v90, v26
	v_exp_f32_e32 v107, v43
	v_exp_f32_e32 v91, v27
	v_exp_f32_e32 v108, v44
	v_exp_f32_e32 v92, v28
	v_exp_f32_e32 v109, v45
	v_exp_f32_e32 v93, v29
	v_exp_f32_e32 v110, v46
	v_exp_f32_e32 v94, v30
	v_exp_f32_e32 v111, v47
	v_exp_f32_e32 v95, v31
	v_exp_f32_e32 v112, v48
	v_exp_f32_e32 v96, v32
	v_exp_f32_e32 v113, v49
	v_exp_f32_e32 v97, v33
	v_exp_f32_e32 v114, v50
	v_exp_f32_e32 v98, v34
	v_exp_f32_e32 v115, v51
	v_exp_f32_e32 v99, v35
	v_cmp_gt_u32_e32 vcc, 2, v224
	v_and_b32_e32 v2, 3, v6
	s_mov_b32 s59, 1
	v_add_u32_e32 v226, 4, v234
	s_mov_b32 s60, 2
	v_lshlrev_b32_e32 v206, 4, v2
	s_cbranch_vccnz .LBB0_466
	v_mov_b32_e32 v221, v3
	s_lshl_b64 s[6:7], s[4:5], 1
	v_lshl_add_u64 v[4:5], s[6:7], 0, v[220:221]
	s_lshl_b32 s6, s1, 8
	v_mov_b32_e32 v207, v3
	s_and_b32 s6, s6, 0xc000
	v_lshl_add_u64 v[4:5], v[4:5], 0, v[206:207]
	v_lshl_or_b32 v2, v208, 10, s6
	v_lshl_add_u64 v[4:5], v[4:5], 0, v[2:3]
	v_mov_b32_e32 v225, 0
	s_mov_b32 s16, 8
	v_lshl_add_u64 v[8:9], s[94:95], 0, v[4:5]
	s_mov_b32 s11, 0
	s_mov_b64 s[6:7], 0
	v_mov_b32_e32 v68, 0
	v_mov_b32_e32 v69, v225
	v_mov_b32_e32 v70, v225
	v_mov_b32_e32 v71, v225
	v_mov_b32_e32 v72, v225
	v_mov_b32_e32 v73, v225
	v_mov_b32_e32 v74, v225
	v_mov_b32_e32 v75, v225
	v_mov_b32_e32 v76, v225
	v_mov_b32_e32 v77, v225
	v_mov_b32_e32 v78, v225
	v_mov_b32_e32 v79, v225
	v_mov_b32_e32 v80, v225
	v_mov_b32_e32 v81, v225
	v_mov_b32_e32 v82, v225
	v_mov_b32_e32 v83, v225
	v_mov_b32_e32 v52, 0
	v_mov_b32_e32 v53, v225
	v_mov_b32_e32 v54, v225
	v_mov_b32_e32 v55, v225
	v_mov_b32_e32 v56, v225
	v_mov_b32_e32 v57, v225
	v_mov_b32_e32 v58, v225
	v_mov_b32_e32 v59, v225
	v_mov_b32_e32 v60, v225
	v_mov_b32_e32 v61, v225
	v_mov_b32_e32 v62, v225
	v_mov_b32_e32 v63, v225
	v_mov_b32_e32 v64, v225
	v_mov_b32_e32 v65, v225
	v_mov_b32_e32 v66, v225
	v_mov_b32_e32 v67, v225
	v_mov_b32_e32 v36, 0
	v_mov_b32_e32 v37, v225
	v_mov_b32_e32 v38, v225
	v_mov_b32_e32 v39, v225
	v_mov_b32_e32 v40, v225
	v_mov_b32_e32 v41, v225
	v_mov_b32_e32 v42, v225
	v_mov_b32_e32 v43, v225
	v_mov_b32_e32 v44, v225
	v_mov_b32_e32 v45, v225
	v_mov_b32_e32 v46, v225
	v_mov_b32_e32 v47, v225
	v_mov_b32_e32 v48, v225
	v_mov_b32_e32 v49, v225
	v_mov_b32_e32 v50, v225
	v_mov_b32_e32 v51, v225
	v_mov_b32_e32 v20, 0
	v_mov_b32_e32 v21, v225
	v_mov_b32_e32 v22, v225
	v_mov_b32_e32 v23, v225
	v_mov_b32_e32 v24, v225
	v_mov_b32_e32 v25, v225
	v_mov_b32_e32 v26, v225
	v_mov_b32_e32 v27, v225
	v_mov_b32_e32 v28, v225
	v_mov_b32_e32 v29, v225
	v_mov_b32_e32 v30, v225
	v_mov_b32_e32 v31, v225
	v_mov_b32_e32 v32, v225
	v_mov_b32_e32 v33, v225
	v_mov_b32_e32 v34, v225
	v_mov_b32_e32 v35, v225
	v_readfirstlane_b32 s100, v8
	v_readfirstlane_b32 s101, v9
	s_nop 1
	v_subrev_u32_e32 v255, s100, v8
	v_subrev_u32_e32 v254, s100, v204
.LBB0_463:
	s_mov_b32 s8, s60
	s_mov_b32 s9, s16
	s_mov_b32 s10, s59
	ds_read_b128 v[4:7], v219 offset:1024
	v_lshl_add_u32 v207, s11, 14, v214
	v_add_f32_e32 v2, v100, v101
	v_add_f32_e32 v2, v102, v2
	v_add_f32_e32 v2, v103, v2
	v_add_f32_e32 v2, v104, v2
	v_add_f32_e32 v2, v105, v2
	v_cvt_pk_bf16_f32 v160, v100, v101
	v_cvt_pk_bf16_f32 v161, v102, v103
	s_waitcnt lgkmcnt(1)
	v_mfma_f32_32x32x16_bf16 v[132:147], v[192:195], v[116:119], 0
	v_mfma_f32_32x32x16_bf16 v[116:131], v[184:187], v[116:119], 0
	v_add_f32_e32 v2, v106, v2
	v_add_f32_e32 v2, v107, v2
	v_add_f32_e32 v2, v108, v2
	v_add_f32_e32 v2, v109, v2
	v_cvt_pk_bf16_f32 v162, v104, v105
	v_cvt_pk_bf16_f32 v163, v106, v107
	ds_read_b128 v[10:13], v219 offset:2048
	ds_read_b64_tr_b16 v[14:15], v207 offset:24576
	ds_read_b64_tr_b16 v[16:17], v207 offset:25088
	v_add_f32_e32 v2, v110, v2
	v_add_f32_e32 v2, v111, v2
	v_add_f32_e32 v2, v112, v2
	v_add_f32_e32 v2, v113, v2
	v_cvt_pk_bf16_f32 v156, v108, v109
	v_cvt_pk_bf16_f32 v157, v110, v111
	s_waitcnt lgkmcnt(3)
	v_mfma_f32_32x32x16_bf16 v[132:147], v[188:191], v[4:7], v[132:147]
	v_mfma_f32_32x32x16_bf16 v[116:131], v[180:183], v[4:7], v[116:131]
	v_add_f32_e32 v2, v114, v2
	v_add_f32_e32 v2, v115, v2
	v_add_f32_e32 v2, v84, v2
	v_add_f32_e32 v2, v85, v2
	v_cvt_pk_bf16_f32 v158, v112, v113
	v_cvt_pk_bf16_f32 v159, v114, v115
	ds_read_b128 v[4:7], v219 offset:3072
	ds_read_b64_tr_b16 v[100:101], v207 offset:28672
	ds_read_b64_tr_b16 v[102:103], v207 offset:29184
	v_add_f32_e32 v2, v86, v2
	v_add_f32_e32 v2, v87, v2
	v_add_f32_e32 v2, v88, v2
	v_add_f32_e32 v2, v89, v2
	v_cvt_pk_bf16_f32 v152, v84, v85
	v_cvt_pk_bf16_f32 v153, v86, v87
	s_waitcnt lgkmcnt(5)
	v_mfma_f32_32x32x16_bf16 v[132:147], v[176:179], v[10:13], v[132:147]
	v_mfma_f32_32x32x16_bf16 v[116:131], v[172:175], v[10:13], v[116:131]
	v_add_f32_e32 v2, v90, v2
	v_add_f32_e32 v2, v91, v2
	v_add_f32_e32 v2, v92, v2
	v_add_f32_e32 v2, v93, v2
	v_cvt_pk_bf16_f32 v154, v88, v89
	v_cvt_pk_bf16_f32 v155, v90, v91
	ds_read_b64_tr_b16 v[84:85], v207 offset:25600
	ds_read_b64_tr_b16 v[86:87], v207 offset:26112
	v_add_f32_e32 v2, v94, v2
	v_add_f32_e32 v2, v95, v2
	v_add_f32_e32 v2, v96, v2
	v_add_f32_e32 v2, v97, v2
	v_cvt_pk_bf16_f32 v148, v92, v93
	v_cvt_pk_bf16_f32 v149, v94, v95
	s_waitcnt lgkmcnt(4)
	v_mfma_f32_32x32x16_bf16 v[132:147], v[168:171], v[4:7], v[132:147]
	v_mfma_f32_32x32x16_bf16 v[116:131], v[164:167], v[4:7], v[116:131]
	v_add_f32_e32 v2, v98, v2
	v_add_f32_e32 v2, v99, v2
	v_cvt_pk_bf16_f32 v150, v96, v97
	v_cvt_pk_bf16_f32 v151, v98, v99
	v_add_f32_e32 v2, v225, v2
	ds_read_b64_tr_b16 v[4:5], v207 offset:29696
	ds_read_b64_tr_b16 v[6:7], v207 offset:30208
	v_mfma_f32_32x32x16_bf16 v[68:83], v[160:163], v[14:17], v[68:83]
	v_exp_f32_e32 v132, v132
	v_exp_f32_e32 v133, v133
	ds_read_b64_tr_b16 v[14:15], v207 offset:26624
	ds_read_b64_tr_b16 v[16:17], v207 offset:27136
	s_waitcnt lgkmcnt(6)
	v_mfma_f32_32x32x16_bf16 v[52:67], v[160:163], v[100:103], v[52:67]
	v_exp_f32_e32 v134, v134
	v_exp_f32_e32 v135, v135
	s_add_u32 s98, s6, s28
	s_addc_u32 s99, s7, s29
	s_add_u32 s98, s98, s100
	s_addc_u32 s99, s99, s101
	s_lshl_b32 m0, s59, 13
	s_add_i32 m0, m0, s49
	s_nop 0
	global_load_lds_dwordx4 v254, s[98:99]
	ds_read_b64_tr_b16 v[88:89], v207 offset:30720
	ds_read_b64_tr_b16 v[90:91], v207 offset:31232
	s_waitcnt lgkmcnt(6)
	v_mfma_f32_32x32x16_bf16 v[68:83], v[156:159], v[84:87], v[68:83]
	v_exp_f32_e32 v136, v136
	v_exp_f32_e32 v137, v137
	ds_read_b64_tr_b16 v[84:85], v207 offset:27648
	ds_read_b64_tr_b16 v[86:87], v207 offset:28160
	s_waitcnt lgkmcnt(6)
	v_mfma_f32_32x32x16_bf16 v[52:67], v[156:159], v[4:7], v[52:67]
	v_exp_f32_e32 v138, v138
	v_exp_f32_e32 v139, v139
	ds_read_b64_tr_b16 v[4:5], v207 offset:31744
	ds_read_b64_tr_b16 v[6:7], v207 offset:32256
	s_waitcnt lgkmcnt(6)
	v_mfma_f32_32x32x16_bf16 v[68:83], v[152:155], v[14:17], v[68:83]
	v_exp_f32_e32 v140, v140
	v_exp_f32_e32 v141, v141
	s_add_u32 s98, s6, s30
	s_addc_u32 s99, s7, s31
	s_add_u32 s98, s98, s100
	s_addc_u32 s99, s99, s101
	s_lshl_b32 m0, s60, 14
	s_add_i32 m0, m0, s58
	s_nop 0
	global_load_lds_dwordx4 v255, s[98:99]
	ds_read_b64_tr_b16 v[14:15], v207 offset:32768
	ds_read_b64_tr_b16 v[16:17], v207 offset:33280
	s_waitcnt lgkmcnt(6)
	v_mfma_f32_32x32x16_bf16 v[52:67], v[152:155], v[88:91], v[52:67]
	v_exp_f32_e32 v142, v142
	v_exp_f32_e32 v143, v143
	ds_read_b64_tr_b16 v[88:89], v207 offset:36864
	ds_read_b64_tr_b16 v[90:91], v207 offset:37376
	s_waitcnt lgkmcnt(6)
	v_mfma_f32_32x32x16_bf16 v[68:83], v[148:151], v[84:87], v[68:83]
	v_exp_f32_e32 v144, v144
	v_exp_f32_e32 v145, v145
	ds_read_b64_tr_b16 v[84:85], v207 offset:33792
	ds_read_b64_tr_b16 v[86:87], v207 offset:34304
	s_waitcnt lgkmcnt(6)
	v_mfma_f32_32x32x16_bf16 v[52:67], v[148:151], v[4:7], v[52:67]
	v_exp_f32_e32 v146, v146
	v_exp_f32_e32 v147, v147
	ds_read_b64_tr_b16 v[92:93], v207 offset:37888
	ds_read_b64_tr_b16 v[94:95], v207 offset:38400
	s_lshl_b32 s11, s60, 13
	v_add_u32_e32 v4, s11, v222
	ds_read_b128 v[96:99], v4
	ds_read_b128 v[164:167], v4 offset:512
	s_waitcnt lgkmcnt(8)
	v_mfma_f32_32x32x16_bf16 v[36:51], v[160:163], v[14:17], v[36:51]
	v_exp_f32_e32 v116, v116
	v_exp_f32_e32 v117, v117
	ds_read_b64_tr_b16 v[14:15], v207 offset:34816
	ds_read_b64_tr_b16 v[16:17], v207 offset:35328
	ds_read_b128 v[168:171], v4 offset:2048
	ds_read_b128 v[172:175], v4 offset:2560
	s_waitcnt lgkmcnt(10)
	v_mfma_f32_32x32x16_bf16 v[20:35], v[160:163], v[88:91], v[20:35]
	v_exp_f32_e32 v118, v118
	v_exp_f32_e32 v119, v119
	ds_read_b64_tr_b16 v[88:89], v207 offset:38912
	ds_read_b64_tr_b16 v[90:91], v207 offset:39424
	ds_read_b128 v[176:179], v4 offset:4096
	ds_read_b128 v[180:183], v4 offset:4608
	s_waitcnt lgkmcnt(12)
; #define TWAIT_BAR(N) asm volatile("s_waitcnt vmcnt(" #N ") lgkmcnt(0)\n\ts_barrier" ::: "memory")
; #define RESC() do { if constexpr (!NOMAX) if (resc) { asm volatile("s_waitcnt lgkmcnt(0)" ::: "memory"); \
;         _Pragma("unroll") for (int d_ = 0; d_ < 2; ++d_) _Pragma("unroll") for (int r = 0; r < 16; ++r) o[d_][r] *= wsf[crow(r, hi)]; } } while (0)
; #define ROT() do { sl_prev = sl_cur; sl_cur = sl_next; sl_next = (sl_next == 2 * SLOTB) ? 0 : sl_next + SLOTB; } while (0)
; #define RESC() do { if constexpr (!NOMAX) if (resc) { asm volatile("s_waitcnt lgkmcnt(0)" ::: "memory"); \
;         _Pragma("unroll") for (int d_ = 0; d_ < 4; ++d_) _Pragma("unroll") for (int r = 0; r < 16; ++r) o[d_][r] *= wsf[crow(r, hi)]; } } while (0)
; #define ROT() do { sl_prev = sl_cur; sl_cur = sl_next; sl_next = (sl_next == 2) ? 0 : sl_next + 1; } while (0)
; #define RESC() do { if (resc) { asm volatile("s_waitcnt lgkmcnt(0)" ::: "memory"); \
;         _Pragma("unroll") for (int d_ = 0; d_ < 4; ++d_) _Pragma("unroll") for (int r = 0; r < 16; ++r) o[d_][r] *= wsf[crow(r, hi)]; } } while (0)
; template <bool NOMAX>
; __device__ __forceinline__ void diff_unit(const AttnCtx& C, int u, LAS unsigned char* lds) {
;     ...
;     int kk = 1;
;     for (; kk + 7 < n; kk += 2) {
;         STEP(pB0, pB1, pA0, pA1, kk, true, true, true, false);     TWAIT_BAR(3); RESC(); ROT();
;         STEP(pA0, pA1, pB0, pB1, kk + 1, true, true, true, false); TWAIT_BAR(3); RESC(); ROT();
	v_mfma_f32_32x32x16_bf16 v[36:51], v[156:159], v[84:87], v[36:51]
	v_exp_f32_e32 v120, v120
	v_exp_f32_e32 v121, v121
	ds_read_b64_tr_b16 v[84:85], v207 offset:35840
	ds_read_b64_tr_b16 v[86:87], v207 offset:36352
	ds_read_b128 v[184:187], v4 offset:6144
	ds_read_b128 v[4:7], v4 offset:6656
	s_waitcnt lgkmcnt(14)
	v_mfma_f32_32x32x16_bf16 v[20:35], v[156:159], v[92:95], v[20:35]
	v_exp_f32_e32 v122, v122
	v_exp_f32_e32 v123, v123
	ds_read_b64_tr_b16 v[92:93], v207 offset:39936
	ds_read_b64_tr_b16 v[94:95], v207 offset:40448
	s_waitcnt lgkmcnt(12)
	v_mfma_f32_32x32x16_bf16 v[36:51], v[152:155], v[14:17], v[36:51]
	v_exp_f32_e32 v124, v124
	v_exp_f32_e32 v125, v125
	ds_read_b128 v[14:17], v219
	s_waitcnt lgkmcnt(9)
	v_mfma_f32_32x32x16_bf16 v[20:35], v[152:155], v[88:91], v[20:35]
	v_exp_f32_e32 v126, v126
	v_exp_f32_e32 v127, v127
	s_add_u32 s98, s6, s34
	s_addc_u32 s99, s7, s35
	s_add_u32 s98, s98, s100
	s_addc_u32 s99, s99, s101
	s_lshl_b32 m0, s60, 14
	s_add_i32 m0, m0, s58
	s_addk_i32 m0, 0x2000
	s_nop 0
	global_load_lds_dwordx4 v255, s[98:99]
	s_waitcnt lgkmcnt(5)
	v_mfma_f32_32x32x16_bf16 v[36:51], v[148:151], v[84:87], v[36:51]
	v_exp_f32_e32 v128, v128
	v_exp_f32_e32 v129, v129
	s_waitcnt lgkmcnt(1)
	v_mfma_f32_32x32x16_bf16 v[20:35], v[148:151], v[92:95], v[20:35]
	v_exp_f32_e32 v130, v130
	v_exp_f32_e32 v131, v131
	s_waitcnt vmcnt(3) lgkmcnt(0)
	s_barrier
	s_add_i32 s16, s60, 1
	s_cmp_lg_u32 s60, 2
	s_cselect_b32 s59, s16, 0
	ds_read_b128 v[188:191], v219 offset:1024
	v_lshl_add_u32 v207, s10, 14, v214
	s_waitcnt lgkmcnt(1)
	v_mfma_f32_32x32x16_bf16 v[100:115], v[96:99], v[14:17], 0
	v_add_f32_e32 v84, v132, v133
	v_add_f32_e32 v84, v134, v84
	v_add_f32_e32 v84, v135, v84
	v_add_f32_e32 v84, v136, v84
	v_add_f32_e32 v84, v137, v84
	v_cvt_pk_bf16_f32 v160, v132, v133
	v_cvt_pk_bf16_f32 v161, v134, v135
	s_nop 0
	v_add_f32_e32 v84, v138, v84
	v_add_f32_e32 v84, v139, v84
	v_add_f32_e32 v84, v140, v84
	v_add_f32_e32 v148, v141, v84
	v_mfma_f32_32x32x16_bf16 v[84:99], v[164:167], v[14:17], 0
	v_cvt_pk_bf16_f32 v162, v136, v137
	v_cvt_pk_bf16_f32 v163, v138, v139
	ds_read_b128 v[14:17], v219 offset:2048
	ds_read_b64_tr_b16 v[132:133], v207 offset:24576
	ds_read_b64_tr_b16 v[134:135], v207 offset:25088
	s_waitcnt lgkmcnt(3)
	v_mfma_f32_32x32x16_bf16 v[100:115], v[168:171], v[188:191], v[100:115]
	v_add_f32_e32 v136, v142, v148
	v_add_f32_e32 v136, v143, v136
	v_add_f32_e32 v136, v144, v136
	v_add_f32_e32 v136, v145, v136
	v_cvt_pk_bf16_f32 v156, v140, v141
	v_cvt_pk_bf16_f32 v157, v142, v143
	v_mfma_f32_32x32x16_bf16 v[84:99], v[172:175], v[188:191], v[84:99]
	v_add_f32_e32 v136, v146, v136
	v_add_f32_e32 v136, v147, v136
	v_add_f32_e32 v136, v116, v136
	v_add_f32_e32 v148, v117, v136
	v_cvt_pk_bf16_f32 v158, v144, v145
	v_cvt_pk_bf16_f32 v159, v146, v147
	ds_read_b128 v[136:139], v219 offset:3072
	ds_read_b64_tr_b16 v[140:141], v207 offset:28672
	ds_read_b64_tr_b16 v[142:143], v207 offset:29184
	s_waitcnt lgkmcnt(5)
	v_mfma_f32_32x32x16_bf16 v[100:115], v[176:179], v[14:17], v[100:115]
	v_add_f32_e32 v144, v118, v148
	v_add_f32_e32 v144, v119, v144
	v_add_f32_e32 v144, v120, v144
	v_add_f32_e32 v144, v121, v144
	v_cvt_pk_bf16_f32 v152, v116, v117
	v_cvt_pk_bf16_f32 v153, v118, v119
	v_mfma_f32_32x32x16_bf16 v[84:99], v[180:183], v[14:17], v[84:99]
	v_add_f32_e32 v14, v122, v144
	v_add_f32_e32 v14, v123, v14
	v_add_f32_e32 v14, v124, v14
	v_add_f32_e32 v116, v125, v14
	v_cvt_pk_bf16_f32 v154, v120, v121
	v_cvt_pk_bf16_f32 v155, v122, v123
	ds_read_b64_tr_b16 v[14:15], v207 offset:25600
	ds_read_b64_tr_b16 v[16:17], v207 offset:26112
	s_waitcnt lgkmcnt(4)
	v_mfma_f32_32x32x16_bf16 v[100:115], v[184:187], v[136:139], v[100:115]
	v_add_f32_e32 v116, v126, v116
	v_add_f32_e32 v116, v127, v116
	v_add_f32_e32 v116, v128, v116
	v_add_f32_e32 v116, v129, v116
	v_cvt_pk_bf16_f32 v148, v124, v125
	v_cvt_pk_bf16_f32 v149, v126, v127
	v_mfma_f32_32x32x16_bf16 v[84:99], v[4:7], v[136:139], v[84:99]
	v_add_f32_e32 v4, v130, v116
	v_add_f32_e32 v4, v131, v4
	v_cvt_pk_bf16_f32 v150, v128, v129
	v_cvt_pk_bf16_f32 v151, v130, v131
	v_add_f32_e32 v225, v2, v4
	ds_read_b64_tr_b16 v[4:5], v207 offset:29696
	ds_read_b64_tr_b16 v[6:7], v207 offset:30208
	v_mfma_f32_32x32x16_bf16 v[68:83], v[160:163], v[132:135], v[68:83]
	v_exp_f32_e32 v100, v100
	v_exp_f32_e32 v101, v101
	ds_read_b64_tr_b16 v[10:11], v207 offset:26624
	ds_read_b64_tr_b16 v[12:13], v207 offset:27136
	s_waitcnt lgkmcnt(6)
; #define TWAIT_BAR(N) asm volatile("s_waitcnt vmcnt(" #N ") lgkmcnt(0)\n\ts_barrier" ::: "memory")
; #define RESC() do { if constexpr (!NOMAX) if (resc) { asm volatile("s_waitcnt lgkmcnt(0)" ::: "memory"); \
;         _Pragma("unroll") for (int d_ = 0; d_ < 2; ++d_) _Pragma("unroll") for (int r = 0; r < 16; ++r) o[d_][r] *= wsf[crow(r, hi)]; } } while (0)
; #define ROT() do { sl_prev = sl_cur; sl_cur = sl_next; sl_next = (sl_next == 2 * SLOTB) ? 0 : sl_next + SLOTB; } while (0)
; #define RESC() do { if constexpr (!NOMAX) if (resc) { asm volatile("s_waitcnt lgkmcnt(0)" ::: "memory"); \
;         _Pragma("unroll") for (int d_ = 0; d_ < 4; ++d_) _Pragma("unroll") for (int r = 0; r < 16; ++r) o[d_][r] *= wsf[crow(r, hi)]; } } while (0)
; #define ROT() do { sl_prev = sl_cur; sl_cur = sl_next; sl_next = (sl_next == 2) ? 0 : sl_next + 1; } while (0)
; #define RESC() do { if (resc) { asm volatile("s_waitcnt lgkmcnt(0)" ::: "memory"); \
;         _Pragma("unroll") for (int d_ = 0; d_ < 4; ++d_) _Pragma("unroll") for (int r = 0; r < 16; ++r) o[d_][r] *= wsf[crow(r, hi)]; } } while (0)
; template <bool NOMAX>
; __device__ __forceinline__ void diff_unit(const AttnCtx& C, int u, LAS unsigned char* lds) {
;     ...
;     int kk = 1;
;     for (; kk + 7 < n; kk += 2) {
;         STEP(pB0, pB1, pA0, pA1, kk, true, true, true, false);     TWAIT_BAR(3); RESC(); ROT();
;         STEP(pA0, pA1, pB0, pB1, kk + 1, true, true, true, false); TWAIT_BAR(3); RESC(); ROT();
;     }
	v_mfma_f32_32x32x16_bf16 v[52:67], v[160:163], v[140:143], v[52:67]
	v_exp_f32_e32 v102, v102
	v_exp_f32_e32 v103, v103
	s_add_u32 s98, s6, s36
	s_addc_u32 s99, s7, s37
	s_add_u32 s98, s98, s100
	s_addc_u32 s99, s99, s101
	s_lshl_b32 m0, s60, 13
	s_add_i32 m0, m0, s49
	s_nop 0
	global_load_lds_dwordx4 v254, s[98:99]
	ds_read_b64_tr_b16 v[116:117], v207 offset:30720
	ds_read_b64_tr_b16 v[118:119], v207 offset:31232
	s_waitcnt lgkmcnt(6)
	v_mfma_f32_32x32x16_bf16 v[68:83], v[156:159], v[14:17], v[68:83]
	v_exp_f32_e32 v104, v104
	v_exp_f32_e32 v105, v105
	ds_read_b64_tr_b16 v[14:15], v207 offset:27648
	ds_read_b64_tr_b16 v[16:17], v207 offset:28160
	s_waitcnt lgkmcnt(6)
	v_mfma_f32_32x32x16_bf16 v[52:67], v[156:159], v[4:7], v[52:67]
	v_exp_f32_e32 v106, v106
	v_exp_f32_e32 v107, v107
	ds_read_b64_tr_b16 v[4:5], v207 offset:31744
	ds_read_b64_tr_b16 v[6:7], v207 offset:32256
	s_waitcnt lgkmcnt(6)
	v_mfma_f32_32x32x16_bf16 v[68:83], v[152:155], v[10:13], v[68:83]
	v_exp_f32_e32 v108, v108
	v_exp_f32_e32 v109, v109
	s_add_u32 s98, s6, s38
	s_addc_u32 s99, s7, s39
	s_add_u32 s98, s98, s100
	s_addc_u32 s99, s99, s101
	s_lshl_b32 m0, s59, 14
	s_add_i32 m0, m0, s58
	s_nop 0
	global_load_lds_dwordx4 v255, s[98:99]
	ds_read_b64_tr_b16 v[10:11], v207 offset:32768
	ds_read_b64_tr_b16 v[12:13], v207 offset:33280
	s_waitcnt lgkmcnt(6)
	v_mfma_f32_32x32x16_bf16 v[52:67], v[152:155], v[116:119], v[52:67]
	v_exp_f32_e32 v110, v110
	v_exp_f32_e32 v111, v111
	ds_read_b64_tr_b16 v[116:117], v207 offset:36864
	ds_read_b64_tr_b16 v[118:119], v207 offset:37376
	s_waitcnt lgkmcnt(6)
	v_mfma_f32_32x32x16_bf16 v[68:83], v[148:151], v[14:17], v[68:83]
	v_exp_f32_e32 v112, v112
	v_exp_f32_e32 v113, v113
	ds_read_b64_tr_b16 v[14:15], v207 offset:33792
	ds_read_b64_tr_b16 v[16:17], v207 offset:34304
	s_waitcnt lgkmcnt(6)
	v_mfma_f32_32x32x16_bf16 v[52:67], v[148:151], v[4:7], v[52:67]
	v_exp_f32_e32 v114, v114
	v_exp_f32_e32 v115, v115
	ds_read_b64_tr_b16 v[4:5], v207 offset:37888
	ds_read_b64_tr_b16 v[6:7], v207 offset:38400
	v_lshl_add_u32 v2, s59, 13, v222
	ds_read_b128 v[192:195], v2
	ds_read_b128 v[184:187], v2 offset:512
	s_waitcnt lgkmcnt(8)
	v_mfma_f32_32x32x16_bf16 v[36:51], v[160:163], v[10:13], v[36:51]
	v_exp_f32_e32 v84, v84
	v_exp_f32_e32 v85, v85
	ds_read_b64_tr_b16 v[10:11], v207 offset:34816
	ds_read_b64_tr_b16 v[12:13], v207 offset:35328
	ds_read_b128 v[188:191], v2 offset:2048
	ds_read_b128 v[180:183], v2 offset:2560
	s_waitcnt lgkmcnt(10)
	v_mfma_f32_32x32x16_bf16 v[20:35], v[160:163], v[116:119], v[20:35]
	v_exp_f32_e32 v86, v86
	v_exp_f32_e32 v87, v87
	ds_read_b64_tr_b16 v[120:121], v207 offset:38912
	ds_read_b64_tr_b16 v[122:123], v207 offset:39424
	ds_read_b128 v[176:179], v2 offset:4096
	ds_read_b128 v[172:175], v2 offset:4608
	s_waitcnt lgkmcnt(12)
	v_mfma_f32_32x32x16_bf16 v[36:51], v[156:159], v[14:17], v[36:51]
	v_exp_f32_e32 v88, v88
	v_exp_f32_e32 v89, v89
	ds_read_b64_tr_b16 v[14:15], v207 offset:35840
	ds_read_b64_tr_b16 v[16:17], v207 offset:36352
	ds_read_b128 v[168:171], v2 offset:6144
	ds_read_b128 v[164:167], v2 offset:6656
	s_waitcnt lgkmcnt(14)
	v_mfma_f32_32x32x16_bf16 v[20:35], v[156:159], v[4:7], v[20:35]
	v_exp_f32_e32 v90, v90
	v_exp_f32_e32 v91, v91
	ds_read_b64_tr_b16 v[4:5], v207 offset:39936
	ds_read_b64_tr_b16 v[6:7], v207 offset:40448
	s_waitcnt lgkmcnt(12)
	v_mfma_f32_32x32x16_bf16 v[36:51], v[152:155], v[10:13], v[36:51]
	v_exp_f32_e32 v92, v92
	v_exp_f32_e32 v93, v93
	ds_read_b128 v[116:119], v219
	s_waitcnt lgkmcnt(9)
	v_mfma_f32_32x32x16_bf16 v[20:35], v[152:155], v[120:123], v[20:35]
	v_exp_f32_e32 v94, v94
	v_exp_f32_e32 v95, v95
	s_add_u32 s98, s6, s40
	s_addc_u32 s99, s7, s41
	s_add_u32 s98, s98, s100
	s_addc_u32 s99, s99, s101
	s_lshl_b32 m0, s59, 14
	s_add_i32 m0, m0, s58
	s_addk_i32 m0, 0x2000
	s_nop 0
	global_load_lds_dwordx4 v255, s[98:99]
	s_waitcnt lgkmcnt(5)
	v_mfma_f32_32x32x16_bf16 v[36:51], v[148:151], v[14:17], v[36:51]
	v_exp_f32_e32 v96, v96
	v_exp_f32_e32 v97, v97
	s_waitcnt lgkmcnt(1)
	v_mfma_f32_32x32x16_bf16 v[20:35], v[148:151], v[4:7], v[20:35]
	v_exp_f32_e32 v98, v98
	v_exp_f32_e32 v99, v99
	s_add_i32 s10, s59, 1
	s_cmp_lg_u32 s59, 2
	s_waitcnt vmcnt(3) lgkmcnt(0)
	s_barrier
	s_cselect_b32 s60, s10, 0
	s_add_i32 s16, s9, 2
	s_add_u32 s6, s6, 0x20000
	v_cmp_ge_u32_e32 vcc, s16, v226
	s_addc_u32 s7, s7, 0
	s_mov_b32 s11, s8
	s_cbranch_vccz .LBB0_463
	s_add_i32 s16, s9, -5
	s_branch .LBB0_467
